# ssd scan rewritten in chunked SSD form on the f32 matrix cores (v_mfma_f32_16x16x4_f32, f32 in/acc), split barrier, 3-deep prefetch; ret/lru/conv/PREP-tail all beside ssd units
# baseline (speedup 1.0000x reference)
; __device__ __forceinline__ void run_phase(CP p, int ph, char* smem_full) {
;     ...
;     case 3: {
;       for (int u = vb; u < 320; u += NVB) {
;         if (u < 128) { for (int rr_ = 0; rr_ < ((SCAN_REP >> 0) & 1) + 1; ++rr_) rwkv_scan_unit(p, u, smem); }
;         else if (u < 256) { for (int rr_ = 0; rr_ < ((SCAN_REP >> 1) & 1) + 1; ++rr_) ssd_scan_unit(p, l, u - 128, smem); }
;         else if (u < 272) ret_mfma_unit(p, l, u - 256, smem);
;         else if (u < 288) { }
;         else if (u < 320) { for (int rr_ = 0; rr_ < ((SCAN_REP >> 3) & 1) + 1; ++rr_) lru_scan_unit(p, u - 288, smem); }
;       }
.LBB0_391:
	s_andn2_b64 vcc, exec, s[2:3]
	s_cbranch_vccnz .LBB0_649
	s_cmpk_eq_i32 s46, 0x100
	s_cbranch_scc0 .Lmap_done
	s_cmpk_lt_i32 s54, 0x100
	s_cbranch_scc1 .Lmap_done
	s_sub_i32 s0, s54, 0x100
	s_cmpk_lt_i32 s0, 0x80
	s_cbranch_scc0 .Lmap_a
	s_movk_i32 s54, 0x110
	s_branch .Lmap_done

; __device__ __forceinline__ void run_phase(CP p, int ph, char* smem_full) {
;     ...
;     case 3: {
;       for (int u = vb; u < 320; u += NVB) {
;         if (u < 128) { for (int rr_ = 0; rr_ < ((SCAN_REP >> 0) & 1) + 1; ++rr_) rwkv_scan_unit(p, u, smem); }
;         else if (u < 256) { for (int rr_ = 0; rr_ < ((SCAN_REP >> 1) & 1) + 1; ++rr_) ssd_scan_unit(p, l, u - 128, smem); }
;         else if (u < 272) ret_mfma_unit(p, l, u - 256, smem);
;         else if (u < 288) { }
;         else if (u < 320) { for (int rr_ = 0; rr_ < ((SCAN_REP >> 3) & 1) + 1; ++rr_) lru_scan_unit(p, u - 288, smem); }
;       }
;       {
;         const int nwork = NVB > 320 ? NVB - 320 : NVB;
;         const int wk = NVB > 320 ? vb - 320 : vb;
;         const int ngu = 16 * 44;
;         if (wk >= 0) {
;           for (int id = wk; id < 256 + 2 * ngu + 44 * 16; id += nwork) {
;             if (id < 256) conv_tile(p.in[7] + (size_t)l * D * D, WO, D, D, (id % 16) * 64, (id / 16) * 64, 0, smem);
;             else if (id < 256 + ngu) { const int k = id - 256; conv_tile(p.in[33] + (size_t)l * D * DFF, WA, D, DFF, (k % 16) * 64, (k / 16) * 64, 1, smem); }
;             else if (id < 256 + 2 * ngu) { const int k = id - 256 - ngu; conv_tile(p.in[34] + (size_t)l * D * DFF, WA, D, DFF, (k % 16) * 64, (k / 16) * 64, 2, smem); }
;             else { const int k = id - 256 - 2 * ngu; conv_tile(p.in[35] + (size_t)l * DFF * D, WB, DFF, D, (k % 44) * 64, (k / 44) * 64, 0, smem); }
;           }
;         }
;       }
.Lmap_c:
	s_cmpk_lt_i32 s0, 0xb8
	s_cbranch_scc0 .Lmap_d
	s_add_i32 s54, s0, 0x350
	s_branch .Lprep_entry
.Lmap_d:
	s_add_i32 s54, s0, 0x88

; __device__ __forceinline__ float bf2f(bf16_t v) { return __uint_as_float(((unsigned)v) << 16); }
; __device__ __forceinline__ float lo2f(unsigned w) { return __uint_as_float(w << 16); }
; __device__ __forceinline__ float hi2f(unsigned w) { return __uint_as_float(w & 0xffff0000u); }
; __device__ __forceinline__ void ssd_scan_unit(CP p, int l, int u, char* smem) {
;   constexpr int SST = 296;
;   float* buf = (float*)smem;
;   const int tid = tidx(), wid = tid >> 6, lane = tid & 63, i = lane >> 4, j = lane & 15;
;   const int b = u >> 4, h = (u >> 2) & 3, q = u & 3, g = h >> 1;
;   const int prow = wid * 4 + i;
;   const bf16_t* SS = (const bf16_t*)(p.ws + WS_SS);
;   const float* SD = (const float*)(p.ws + WS_SD);
;   bf16_t* Y = (bf16_t*)(p.ws + WS_Y);
;   const float Ah = -__expf(p.in[11][l * 4 + h]);
;   const float Dh = p.in[12][l * 4 + h];
;   float hs[8];
; #pragma unroll
;   for (int n = 0; n < 8; ++n) hs[n] = 0.f;
;   uint4 st[2];
;   unsigned short stxr = 0;
;   float stdt = 0.f;
;   auto gload = [&](int c) {
;     const int rb = rowof(b, c * 16);
; #pragma unroll
;     for (int x = 0; x < 2; ++x) {
;       const int e = tid + x * 256, tok = e >> 5, rem = e & 31, which = rem >> 4, part = rem & 15;
;       st[x] = *reinterpret_cast<const uint4*>(SS + (size_t)(rb + tok) * 768 + 256 + which * 256 + g * 128 + part * 8);
;     }
;     {
;       const int tok = tid >> 4, pp = tid & 15;
;       stxr = SS[(size_t)(rb + tok) * 768 + h * 64 + q * 16 + pp];
;       stdt = SD[(size_t)(rb + tok) * 4 + h];
;     }
;   };
;   auto lwrite = [&](int bi) {
; #pragma unroll
;     for (int x = 0; x < 2; ++x) {
;       const int e = tid + x * 256, tok = e >> 5, rem = e & 31, which = rem >> 4, part = rem & 15;
;       float* d = buf + bi * 16 * SST + tok * SST + which * 128 + part * 8;
;       *reinterpret_cast<float4*>(d) = make_float4(lo2f(st[x].x), hi2f(st[x].x), lo2f(st[x].y), hi2f(st[x].y));
;       *reinterpret_cast<float4*>(d + 4) = make_float4(lo2f(st[x].z), hi2f(st[x].z), lo2f(st[x].w), hi2f(st[x].w));
;     }
;     {
;       const int tok = tid >> 4, pp = tid & 15;
;       float* d = buf + bi * 16 * SST + tok * SST;
;       const float stx = bf2f(stxr);
;       d[256 + pp] = stx * stdt;
;       d[272 + pp] = stx;
;       if (pp == 0) d[288] = __expf(stdt * Ah);
;     }
;   };
;   half_barrier(smem);
;   gload(0);
;   lwrite(0);
;   half_barrier(smem);
.LBB0_542:
	s_or_b64 exec, exec, s[2:3]
	s_lshl_b32 s3, s11, 7
	s_lshl_b32 s2, s28, 6
	s_and_b32 s11, s3, 0x3800
	s_add_i32 s11, s11, -16
	s_lshl_b32 s2, s2, 1
	v_readlane_b32 s4, v254, 7
	v_mov_b32_e32 v11, v149
	v_readlane_b32 s5, v254, 8
	s_add_u32 s2, s4, s2
	v_lshrrev_b32_e32 v9, 4, v12
	v_lshl_add_u64 v[26:27], s[72:73], 0, v[10:11]
	v_lshl_add_u64 v[10:11], s[44:45], 0, v[148:149]
	s_addc_u32 s3, s5, 0
	v_bfe_u32 v12, v12, 4, 2
	v_bfi_b32 v24, -4, v45, v9
	v_lshl_add_u64 v[10:11], v[10:11], 0, s[80:81]
	v_mov_b32_e32 v9, v149
	s_add_u32 s2, s2, s29
	v_lshl_add_u64 v[30:31], v[10:11], 0, v[8:9]
	v_lshlrev_b32_e32 v8, 2, v45
	v_lshlrev_b32_e32 v9, 2, v12
	s_addc_u32 s3, s3, 0
	v_ashrrev_i32_e32 v25, 31, v24
	v_and_or_b32 v8, v8, -16, v9
	v_mov_b32_e32 v32, 0
	v_lshlrev_b32_e32 v56, 2, v44
	v_lshl_add_u64 v[28:29], v[24:25], 1, s[2:3]
	v_add_u32_e32 v25, 0x8a0, v8
	v_lshlrev_b32_e32 v57, 4, v44
	s_mov_b32 s4, 0
	s_mov_b64 s[72:73], 0
	v_mov_b32_e32 v33, v32
	v_mov_b32_e32 v38, v32
	v_mov_b32_e32 v39, v32
	v_mov_b32_e32 v36, v32
	v_mov_b32_e32 v37, v32
	v_mov_b32_e32 v34, v32
	v_mov_b32_e32 v35, v32
	v_lshrrev_b32_e32 v16, 6, v214
	v_lshrrev_b32_e32 v17, 4, v217
	v_and_b32_e32 v19, 15, v217
	v_lshlrev_b32_e32 v20, 7, v16
	v_mul_u32_u24_e32 v60, 0x210, v19
	v_add_u32_e32 v60, v60, v20
	v_lshl_add_u32 v60, v17, 4, v60
	v_mul_u32_u24_e32 v61, 0x840, v17
	v_add_u32_e32 v61, v61, v20
	v_lshl_add_u32 v61, v19, 2, v61
	v_mul_u32_u24_e32 v62, 0x140, v17
	v_lshl_add_u32 v62, v19, 2, v62
	v_lshlrev_b32_e32 v63, 2, v19
	v_lshlrev_b32_e32 v66, 6, v16
	v_add_u32_e32 v66, 19520, v66
	v_add_u32_e32 v64, v66, v63
	v_lshl_add_u32 v65, v17, 4, v66
	v_lshlrev_b32_e32 v67, 10, v16
	v_lshl_add_u32 v67, v19, 6, v67
	v_lshl_add_u32 v67, v17, 4, v67
	v_lshlrev_b32_e32 v68, 6, v45
	v_lshl_add_u32 v68, v44, 2, v68
	v_and_b32_e32 v21, 1, v45
	v_mul_u32_u24_e32 v21, 0x2100, v21
	v_lshl_add_u32 v21, v44, 5, v21
	v_mul_u32_u24_e32 v69, 0x210, v47
	v_add_u32_e32 v69, v69, v21
	v_mul_u32_u24_e32 v70, 0x210, v48
	v_add_u32_e32 v70, v70, v21
	v_mul_u32_u24_e32 v71, 0x50, v45
	v_lshl_add_u32 v71, v44, 2, v71
	v_lshlrev_b32_e32 v72, 2, v45
	v_cmp_eq_u32_e32 vcc, 0, v16
	s_nop 1
	v_cndmask_b32_e32 v73, 0, v43, vcc
	v_lshlrev_b32_e32 v20, 2, v17
	v_add_u32_e32 v21, 0, v20
	v_cmp_le_u32_e32 vcc, v21, v19
	s_nop 1
	v_cndmask_b32_e64 v74, 0, -1, vcc
	v_add_u32_e32 v21, 1, v20
	v_cmp_le_u32_e32 vcc, v21, v19
	s_nop 1
	v_cndmask_b32_e64 v75, 0, -1, vcc
	v_add_u32_e32 v21, 2, v20
	v_cmp_le_u32_e32 vcc, v21, v19
	s_nop 1
	v_cndmask_b32_e64 v76, 0, -1, vcc
	v_add_u32_e32 v21, 3, v20
	v_cmp_le_u32_e32 vcc, v21, v19
	s_nop 1
	v_cndmask_b32_e64 v77, 0, -1, vcc
	v_mov_b32_e32 v100, 0
	v_mov_b32_e32 v101, 0
	v_mov_b32_e32 v102, 0
	v_mov_b32_e32 v103, 0
	v_mov_b32_e32 v104, 0
	v_mov_b32_e32 v105, 0
	v_mov_b32_e32 v106, 0
	v_mov_b32_e32 v107, 0
	v_mov_b32_e32 v193, 0x20000
	v_lshl_add_u32 v193, v213, 2, v193
	v_mov_b32_e32 v195, 1
	ds_read_b32 v194, v193 offset:8
	s_waitcnt lgkmcnt(0)
	v_and_b32_e32 v194, -4, v194
	s_mov_b32 s5, s10
	v_add_u32_e32 v8, s5, v45
	v_add_u32_e32 v0, s5, v47
	v_add_u32_e32 v4, s5, v48
	v_ashrrev_i32_e32 v9, 31, v8
	v_mad_i64_i32 v[0:1], s[12:13], v0, s0, v[30:31]
	v_mad_i64_i32 v[4:5], s[12:13], v4, s0, v[30:31]
	v_mad_i64_i32 v[10:11], s[12:13], v8, s0, v[26:27]
	v_lshl_add_u64 v[8:9], v[8:9], 4, s[40:41]
	global_load_dwordx4 v[0:3], v[0:1], off offset:512
	global_load_dwordx4 v[4:7], v[4:5], off offset:512
	global_load_ushort v49, v[10:11], off
	global_load_dword v54, v[8:9], off
	s_mov_b32 s29, s63
	s_waitcnt vmcnt(0)
	v_add_u32_e32 v18, s29, v69
	v_lshlrev_b32_e32 v12, 16, v0
	v_and_b32_e32 v13, 0xffff0000, v0
	v_lshlrev_b32_e32 v14, 16, v1
	v_and_b32_e32 v15, 0xffff0000, v1
	ds_write_b128 v18, v[12:15]
	v_lshlrev_b32_e32 v12, 16, v2
	v_and_b32_e32 v13, 0xffff0000, v2
	v_lshlrev_b32_e32 v14, 16, v3
	v_and_b32_e32 v15, 0xffff0000, v3
	ds_write_b128 v18, v[12:15] offset:16
	v_add_u32_e32 v18, s29, v70
	v_lshlrev_b32_e32 v12, 16, v4
	v_and_b32_e32 v13, 0xffff0000, v4
	v_lshlrev_b32_e32 v14, 16, v5
	v_and_b32_e32 v15, 0xffff0000, v5
	ds_write_b128 v18, v[12:15]
	v_lshlrev_b32_e32 v12, 16, v6
	v_and_b32_e32 v13, 0xffff0000, v6
	v_lshlrev_b32_e32 v14, 16, v7
	v_and_b32_e32 v15, 0xffff0000, v7
	ds_write_b128 v18, v[12:15] offset:16
	v_lshlrev_b32_e32 v9, 16, v49
	v_mul_f32_e32 v10, v54, v9
	v_add_u32_e32 v11, s29, v71
	ds_write_b32 v11, v10 offset:16896
	ds_write_b32 v11, v9 offset:18176
	v_mul_f32_e32 v9, v54, v46
	v_mul_f32_e32 v9, 0xbfb8aa3b, v9
	v_add_u32_e32 v11, s29, v72
	ds_write_b32 v11, v9 offset:19456
	s_add_i32 s5, s11, 16
	v_add_u32_e32 v8, s5, v45
	v_add_u32_e32 v84, s5, v47
	v_add_u32_e32 v88, s5, v48
	v_ashrrev_i32_e32 v9, 31, v8
	v_mad_i64_i32 v[84:85], s[12:13], v84, s0, v[30:31]
	v_mad_i64_i32 v[88:89], s[12:13], v88, s0, v[30:31]
	v_mad_i64_i32 v[10:11], s[12:13], v8, s0, v[26:27]
	v_lshl_add_u64 v[8:9], v[8:9], 4, s[40:41]
	global_load_dwordx4 v[84:87], v[84:85], off offset:512
	global_load_dwordx4 v[88:91], v[88:89], off offset:512
	global_load_ushort v92, v[10:11], off
	global_load_dword v93, v[8:9], off
	s_add_i32 s5, s11, 32
	v_add_u32_e32 v8, s5, v45
	v_add_u32_e32 v184, s5, v47
	v_add_u32_e32 v188, s5, v48
	v_ashrrev_i32_e32 v9, 31, v8
	v_mad_i64_i32 v[184:185], s[12:13], v184, s0, v[30:31]
	v_mad_i64_i32 v[188:189], s[12:13], v188, s0, v[30:31]
	v_mad_i64_i32 v[10:11], s[12:13], v8, s0, v[26:27]
	v_lshl_add_u64 v[8:9], v[8:9], 4, s[40:41]
	global_load_dwordx4 v[184:187], v[184:185], off offset:512
	global_load_dwordx4 v[188:191], v[188:189], off offset:512
	global_load_ushort v94, v[10:11], off
	global_load_dword v95, v[8:9], off
	s_waitcnt lgkmcnt(0)
	s_mov_b64 s[12:13], exec
	s_mov_b64 exec, 1
	ds_add_u32 v193, v195 offset:8
	s_mov_b64 exec, s[12:13]
	v_add_u32_e32 v194, 4, v194

; __device__ __forceinline__ void ssd_scan_unit(CP p, int l, int u, char* smem) {
;     ...
;   constexpr int NCH = T / 16;
;   for (int c = 0; c < NCH; ++c) {
.Lsd_bdone0:
	s_mov_b32 s4, 0

; __device__ __forceinline__ bf16_t f2bf(float f) { return (bf16_t)(pack2(f, 0.f) & 0xffffu); }
; __device__ __forceinline__ void ssd_scan_unit(CP p, int l, int u, char* smem) {
;     ...
;   for (int c = 0; c < NCH; ++c) {
;     if (c + 1 < NCH) gload(c + 1);
;     const float* cb = buf + (c & 1) * 16 * SST;
;     float ykeep = 0.f;
;     float4 B0 = *reinterpret_cast<const float4*>(cb + j * 4), B1 = *reinterpret_cast<const float4*>(cb + 64 + j * 4);
;     float4 C0 = *reinterpret_cast<const float4*>(cb + 128 + j * 4), C1 = *reinterpret_cast<const float4*>(cb + 192 + j * 4);
;     float xdt = cb[256 + prow], xr = cb[272 + prow], a = cb[288];
;     ...
;     Y[(size_t)(rowof(b, c * 16) + j) * 1024 + h * 64 + q * 16 + prow] = f2bf(ykeep);
.Ltw_donesd0:
	s_bitcmp1_b32 s4, 0
	s_cselect_b32 s29, 0x5000, 0
	s_cselect_b32 s58, 0, 0x5000
	s_add_i32 s29, s29, s63
	s_add_i32 s58, s58, s63
	s_add_i32 s59, s63, 0xa000
	s_add_i32 s14, s63, 0xb000
	v_add_u32_e32 v78, s29, v63
	ds_read_b32 v176, v78 offset:19456
	v_add_u32_e32 v79, s29, v60
	ds_read_b128 v[116:119], v79 offset:8448
	ds_read_b128 v[124:127], v79
	ds_read_b128 v[120:123], v79 offset:8512
	ds_read_b128 v[128:131], v79 offset:64
	s_cmp_lt_u32 s4, 2
	s_cbranch_scc1 .Lsd_nofs0
	v_add_u32_e32 v8, s14, v68
	ds_read_b32 v9, v8
	ds_read_b32 v10, v8 offset:1024
	ds_read_b32 v11, v8 offset:2048
	ds_read_b32 v12, v8 offset:3072
	s_add_i32 s5, s4, -2
	s_lshl_b32 s5, s5, 4
	s_add_i32 s5, s5, s11
	s_cmp_eq_u32 s4, 2
	s_cselect_b32 s5, s10, s5
	v_or_b32_e32 v14, s5, v44
	v_ashrrev_i32_e32 v15, 31, v14
	v_lshlrev_b64 v[14:15], 11, v[14:15]
	v_lshl_add_u64 v[14:15], v[28:29], 0, v[14:15]
	s_waitcnt lgkmcnt(0)
	v_add_f32_e32 v9, v9, v10
	v_add_f32_e32 v9, v9, v11
	v_add_f32_e32 v9, v9, v12
	v_cvt_pk_bf16_f32 v9, v9, s0
	global_store_short v[14:15], v9, off
; __device__ __forceinline__ void ssd_scan_unit(CP p, int l, int u, char* smem) {
;     ...
;   auto lwrite = [&](int bi) {
; #pragma unroll
;     for (int x = 0; x < 2; ++x) {
;       const int e = tid + x * 256, tok = e >> 5, rem = e & 31, which = rem >> 4, part = rem & 15;
;       float* d = buf + bi * 16 * SST + tok * SST + which * 128 + part * 8;
;       *reinterpret_cast<float4*>(d) = make_float4(lo2f(st[x].x), hi2f(st[x].x), lo2f(st[x].y), hi2f(st[x].y));
;       *reinterpret_cast<float4*>(d + 4) = make_float4(lo2f(st[x].z), hi2f(st[x].z), lo2f(st[x].w), hi2f(st[x].w));
;     }
;     {
;       const int tok = tid >> 4, pp = tid & 15;
;     ...
;   for (int c = 0; c < NCH; ++c) {
;     if (c + 1 < NCH) gload(c + 1);
;     const float* cb = buf + (c & 1) * 16 * SST;
;     float ykeep = 0.f;
;     float4 B0 = *reinterpret_cast<const float4*>(cb + j * 4), B1 = *reinterpret_cast<const float4*>(cb + 64 + j * 4);
;     float4 C0 = *reinterpret_cast<const float4*>(cb + 128 + j * 4), C1 = *reinterpret_cast<const float4*>(cb + 192 + j * 4);
;     float xdt = cb[256 + prow], xr = cb[272 + prow], a = cb[288];
; #pragma unroll 2
;     for (int s = 0; s < 16; ++s) {
;       const float* sb = cb + (s + 1) * SST;
;       const float4 B0n = *reinterpret_cast<const float4*>(sb + j * 4), B1n = *reinterpret_cast<const float4*>(sb + 64 + j * 4);
;       const float4 C0n = *reinterpret_cast<const float4*>(sb + 128 + j * 4), C1n = *reinterpret_cast<const float4*>(sb + 192 + j * 4);
;       const float xdtn = sb[256 + prow], xrn = sb[272 + prow], an = sb[288];
;       __builtin_amdgcn_sched_barrier(0);
;       hs[0] = fmaf(a, hs[0], xdt * B0.x); hs[1] = fmaf(a, hs[1], xdt * B0.y); hs[2] = fmaf(a, hs[2], xdt * B0.z); hs[3] = fmaf(a, hs[3], xdt * B0.w);
;       hs[4] = fmaf(a, hs[4], xdt * B1.x); hs[5] = fmaf(a, hs[5], xdt * B1.y); hs[6] = fmaf(a, hs[6], xdt * B1.z); hs[7] = fmaf(a, hs[7], xdt * B1.w);
;       float y = hs[0] * C0.x + hs[1] * C0.y + hs[2] * C0.z + hs[3] * C0.w + hs[4] * C1.x + hs[5] * C1.y + hs[6] * C1.z + hs[7] * C1.w;
;       y = allreduce16(y);
;       y = fmaf(Dh, xr, y);
;       if (j == s) ykeep = y;
;       B0 = B0n; B1 = B1n; C0 = C0n; C1 = C1n; xdt = xdtn; xr = xrn; a = an;
;     }
;     Y[(size_t)(rowof(b, c * 16) + j) * 1024 + h * 64 + q * 16 + prow] = f2bf(ykeep);
;     if (c + 1 < NCH) lwrite((c + 1) & 1);
;     half_barrier(smem);
;   }
.Lsd_nofs0:
	s_waitcnt lgkmcnt(0)
	v_mfma_f32_16x16x4_f32 v[108:111], v124, v116, 0
	v_add_f32_dpp v177, v176, v176 row_shr:1 row_mask:0xf bank_mask:0xf bound_ctrl:1
	s_nop 1
	v_add_f32_dpp v178, v177, v177 row_shr:2 row_mask:0xf bank_mask:0xf bound_ctrl:1
	s_nop 1
	v_add_f32_dpp v179, v178, v178 row_shr:4 row_mask:0xf bank_mask:0xf bound_ctrl:1
	s_nop 1
	v_mfma_f32_16x16x4_f32 v[112:115], v116, v100, 0
	v_add_f32_dpp v180, v179, v179 row_shr:8 row_mask:0xf bank_mask:0xf bound_ctrl:1
	v_add_u32_e32 v78, s29, v64
	v_add_u32_e32 v80, s29, v65
	v_add_u32_e32 v81, s29, v66
	ds_write_b32 v78, v180
	ds_read_b128 v[156:159], v80
	v_mfma_f32_16x16x4_f32 v[108:111], v125, v117, v[108:111]
	ds_read_b32 v181, v81 offset:60
	v_add_u32_e32 v82, s29, v61
	v_add_u32_e32 v83, s29, v62
	ds_read_b32 v140, v83 offset:16896
	ds_read_b32 v141, v83 offset:16976
	ds_read_b32 v142, v83 offset:17056
	v_mfma_f32_16x16x4_f32 v[112:115], v117, v101, v[112:115]
	ds_read_b32 v143, v83 offset:17136
	ds_read_b32 v132, v82 offset:0
	ds_read_b32 v133, v82 offset:528
	ds_read_b32 v134, v82 offset:1056
	ds_read_b32 v135, v82 offset:1584
	ds_read_b32 v136, v82 offset:64
	v_mfma_f32_16x16x4_f32 v[108:111], v126, v118, v[108:111]
	ds_read_b32 v137, v82 offset:592
	ds_read_b32 v138, v82 offset:1120
	ds_read_b32 v139, v82 offset:1648
	ds_read_b32 v152, v83 offset:18176
	ds_read_b32 v153, v83 offset:18256
	ds_read_b32 v154, v83 offset:18336
	v_mfma_f32_16x16x4_f32 v[112:115], v118, v102, v[112:115]
	ds_read_b32 v155, v83 offset:18416
	s_waitcnt vmcnt(4)
	v_add_u32_e32 v18, s58, v69
	v_lshlrev_b32_e32 v12, 16, v84
	v_and_b32_e32 v13, 0xffff0000, v84
	v_lshlrev_b32_e32 v14, 16, v85
	v_mfma_f32_16x16x4_f32 v[108:111], v127, v119, v[108:111]
	v_and_b32_e32 v15, 0xffff0000, v85
	ds_write_b128 v18, v[12:15]
	v_lshlrev_b32_e32 v12, 16, v86
	v_and_b32_e32 v13, 0xffff0000, v86
	v_lshlrev_b32_e32 v14, 16, v87
	v_and_b32_e32 v15, 0xffff0000, v87
	v_mfma_f32_16x16x4_f32 v[112:115], v119, v103, v[112:115]
	ds_write_b128 v18, v[12:15] offset:16
	v_add_u32_e32 v18, s58, v70
	v_lshlrev_b32_e32 v12, 16, v88
	v_and_b32_e32 v13, 0xffff0000, v88
	v_lshlrev_b32_e32 v14, 16, v89
	v_and_b32_e32 v15, 0xffff0000, v89
	v_mfma_f32_16x16x4_f32 v[108:111], v128, v120, v[108:111]
	ds_write_b128 v18, v[12:15]
	v_lshlrev_b32_e32 v12, 16, v90
	v_and_b32_e32 v13, 0xffff0000, v90
	v_lshlrev_b32_e32 v14, 16, v91
	v_and_b32_e32 v15, 0xffff0000, v91
	ds_write_b128 v18, v[12:15] offset:16
	v_mfma_f32_16x16x4_f32 v[112:115], v120, v104, v[112:115]
	v_lshlrev_b32_e32 v9, 16, v92
	v_mul_f32_e32 v10, v93, v9
	v_add_u32_e32 v11, s58, v71
	ds_write_b32 v11, v10 offset:16896
	ds_write_b32 v11, v9 offset:18176
	v_mul_f32_e32 v9, v93, v46
	v_mfma_f32_16x16x4_f32 v[108:111], v129, v121, v[108:111]
	v_mul_f32_e32 v9, 0xbfb8aa3b, v9
	v_add_u32_e32 v11, s58, v72
	ds_write_b32 v11, v9 offset:19456
	s_waitcnt lgkmcnt(0)
	s_mov_b64 s[12:13], exec
	s_mov_b64 exec, 1
	ds_add_u32 v193, v195 offset:8
	s_mov_b64 exec, s[12:13]
	v_add_u32_e32 v194, 4, v194
	s_nop 3
	v_exp_f32_e32 v182, v181
	v_mfma_f32_16x16x4_f32 v[112:115], v121, v105, v[112:115]
	v_exp_f32_e32 v160, v156
	v_exp_f32_e32 v161, v157
	v_exp_f32_e32 v162, v158
	v_exp_f32_e32 v163, v159
	v_sub_f32_e32 v164, v181, v156
	v_sub_f32_e32 v165, v181, v157
	v_mfma_f32_16x16x4_f32 v[108:111], v130, v122, v[108:111]
	v_sub_f32_e32 v166, v181, v158
	v_sub_f32_e32 v167, v181, v159
	v_exp_f32_e32 v164, v164
	v_exp_f32_e32 v165, v165
	v_exp_f32_e32 v166, v166
	v_exp_f32_e32 v167, v167
	v_mfma_f32_16x16x4_f32 v[112:115], v122, v106, v[112:115]
	v_sub_f32_e32 v168, v180, v156
	v_sub_f32_e32 v169, v180, v157
	v_sub_f32_e32 v170, v180, v158
	v_sub_f32_e32 v171, v180, v159
	v_exp_f32_e32 v168, v168
	v_exp_f32_e32 v169, v169
	v_mfma_f32_16x16x4_f32 v[108:111], v131, v123, v[108:111]
	v_exp_f32_e32 v170, v170
	v_exp_f32_e32 v171, v171
	s_nop 0
	v_and_b32_e32 v168, v168, v74
	v_and_b32_e32 v169, v169, v75
	v_and_b32_e32 v170, v170, v76
	v_mfma_f32_16x16x4_f32 v[112:115], v123, v107, v[112:115]
	v_and_b32_e32 v171, v171, v77
	v_mul_f32_e32 v144, v164, v140
	v_mul_f32_e32 v145, v165, v141
	v_mul_f32_e32 v146, v166, v142
	v_mul_f32_e32 v147, v167, v143
	v_mul_f32_e32 v100, v182, v100
	v_mul_f32_e32 v101, v182, v101
	v_mul_f32_e32 v102, v182, v102
	v_mul_f32_e32 v103, v182, v103
	v_mul_f32_e32 v104, v182, v104
	v_mul_f32_e32 v105, v182, v105
	v_mul_f32_e32 v106, v182, v106
	v_mul_f32_e32 v107, v182, v107
	v_mul_f32_e32 v172, v108, v168
	v_mul_f32_e32 v173, v109, v169
	v_mul_f32_e32 v174, v110, v170
	v_mul_f32_e32 v175, v111, v171
	s_nop 3
	v_mul_f32_e32 v112, v112, v160
	v_mul_f32_e32 v113, v113, v161
	v_mul_f32_e32 v114, v114, v162
	v_mul_f32_e32 v115, v115, v163
	s_nop 1
	v_mfma_f32_16x16x4_f32 v[100:103], v132, v144, v[100:103]
	s_add_i32 s5, s4, 3
	s_min_i32 s5, s5, 0x80
	v_mfma_f32_16x16x4_f32 v[104:107], v136, v144, v[104:107]
	s_lshl_b32 s5, s5, 4
	s_add_i32 s5, s5, s11
	v_mfma_f32_16x16x4_f32 v[112:115], v172, v140, v[112:115]
	v_add_u32_e32 v8, s5, v45
	v_add_u32_e32 v0, s5, v47
	v_mfma_f32_16x16x4_f32 v[100:103], v133, v145, v[100:103]
	v_add_u32_e32 v4, s5, v48
	v_ashrrev_i32_e32 v9, 31, v8
	v_mfma_f32_16x16x4_f32 v[104:107], v137, v145, v[104:107]
	v_mad_i64_i32 v[0:1], s[12:13], v0, s0, v[30:31]
	v_mad_i64_i32 v[4:5], s[12:13], v4, s0, v[30:31]
	v_mfma_f32_16x16x4_f32 v[112:115], v173, v141, v[112:115]
	v_mad_i64_i32 v[10:11], s[12:13], v8, s0, v[26:27]
	v_lshl_add_u64 v[8:9], v[8:9], 4, s[40:41]
	v_mfma_f32_16x16x4_f32 v[100:103], v134, v146, v[100:103]
	global_load_dwordx4 v[0:3], v[0:1], off offset:512
	global_load_dwordx4 v[4:7], v[4:5], off offset:512
	v_mfma_f32_16x16x4_f32 v[104:107], v138, v146, v[104:107]
	global_load_ushort v49, v[10:11], off
	global_load_dword v54, v[8:9], off
	v_mfma_f32_16x16x4_f32 v[112:115], v174, v142, v[112:115]
	v_mfma_f32_16x16x4_f32 v[100:103], v135, v147, v[100:103]
	v_mfma_f32_16x16x4_f32 v[104:107], v139, v147, v[104:107]
	v_mfma_f32_16x16x4_f32 v[112:115], v175, v143, v[112:115]
	s_nop 7
	s_nop 3
	v_fmac_f32_e32 v112, v73, v152
	v_fmac_f32_e32 v113, v73, v153
	v_fmac_f32_e32 v114, v73, v154
	v_fmac_f32_e32 v115, v73, v155
	v_add_u32_e32 v78, s59, v67
	ds_write_b128 v78, v[112:115]

; __device__ __forceinline__ bf16_t f2bf(float f) { return (bf16_t)(pack2(f, 0.f) & 0xffffu); }
; __device__ __forceinline__ void ssd_scan_unit(CP p, int l, int u, char* smem) {
;     ...
;   for (int c = 0; c < NCH; ++c) {
;     if (c + 1 < NCH) gload(c + 1);
;     const float* cb = buf + (c & 1) * 16 * SST;
;     float ykeep = 0.f;
;     float4 B0 = *reinterpret_cast<const float4*>(cb + j * 4), B1 = *reinterpret_cast<const float4*>(cb + 64 + j * 4);
;     float4 C0 = *reinterpret_cast<const float4*>(cb + 128 + j * 4), C1 = *reinterpret_cast<const float4*>(cb + 192 + j * 4);
;     float xdt = cb[256 + prow], xr = cb[272 + prow], a = cb[288];
;     ...
;     Y[(size_t)(rowof(b, c * 16) + j) * 1024 + h * 64 + q * 16 + prow] = f2bf(ykeep);
.Ltw_donesd1:
	s_bitcmp1_b32 s4, 0
	s_cselect_b32 s29, 0x5000, 0
	s_cselect_b32 s58, 0, 0x5000
	s_add_i32 s29, s29, s63
	s_add_i32 s58, s58, s63
	s_add_i32 s59, s63, 0xb000
	s_add_i32 s14, s63, 0xc000
	v_add_u32_e32 v78, s29, v63
	ds_read_b32 v176, v78 offset:19456
	v_add_u32_e32 v79, s29, v60
	ds_read_b128 v[116:119], v79 offset:8448
	ds_read_b128 v[124:127], v79
	ds_read_b128 v[120:123], v79 offset:8512
	ds_read_b128 v[128:131], v79 offset:64
	s_cmp_lt_u32 s4, 2
	s_cbranch_scc1 .Lsd_nofs1
	v_add_u32_e32 v8, s14, v68
	ds_read_b32 v9, v8
	ds_read_b32 v10, v8 offset:1024
	ds_read_b32 v11, v8 offset:2048
	ds_read_b32 v12, v8 offset:3072
	s_add_i32 s5, s4, -2
	s_lshl_b32 s5, s5, 4
	s_add_i32 s5, s5, s11
	s_cmp_eq_u32 s4, 2
	s_cselect_b32 s5, s10, s5
	v_or_b32_e32 v14, s5, v44
	v_ashrrev_i32_e32 v15, 31, v14
	v_lshlrev_b64 v[14:15], 11, v[14:15]
	v_lshl_add_u64 v[14:15], v[28:29], 0, v[14:15]
	s_waitcnt lgkmcnt(0)
	v_add_f32_e32 v9, v9, v10
	v_add_f32_e32 v9, v9, v11
	v_add_f32_e32 v9, v9, v12
	v_cvt_pk_bf16_f32 v9, v9, s0
	global_store_short v[14:15], v9, off
; __device__ __forceinline__ void ssd_scan_unit(CP p, int l, int u, char* smem) {
;     ...
;   auto lwrite = [&](int bi) {
; #pragma unroll
;     for (int x = 0; x < 2; ++x) {
;       const int e = tid + x * 256, tok = e >> 5, rem = e & 31, which = rem >> 4, part = rem & 15;
;       float* d = buf + bi * 16 * SST + tok * SST + which * 128 + part * 8;
;       *reinterpret_cast<float4*>(d) = make_float4(lo2f(st[x].x), hi2f(st[x].x), lo2f(st[x].y), hi2f(st[x].y));
;       *reinterpret_cast<float4*>(d + 4) = make_float4(lo2f(st[x].z), hi2f(st[x].z), lo2f(st[x].w), hi2f(st[x].w));
;     }
;     {
;       const int tok = tid >> 4, pp = tid & 15;
;     ...
;   for (int c = 0; c < NCH; ++c) {
;     if (c + 1 < NCH) gload(c + 1);
;     const float* cb = buf + (c & 1) * 16 * SST;
;     float ykeep = 0.f;
;     float4 B0 = *reinterpret_cast<const float4*>(cb + j * 4), B1 = *reinterpret_cast<const float4*>(cb + 64 + j * 4);
;     float4 C0 = *reinterpret_cast<const float4*>(cb + 128 + j * 4), C1 = *reinterpret_cast<const float4*>(cb + 192 + j * 4);
;     float xdt = cb[256 + prow], xr = cb[272 + prow], a = cb[288];
; #pragma unroll 2
;     for (int s = 0; s < 16; ++s) {
;       const float* sb = cb + (s + 1) * SST;
;       const float4 B0n = *reinterpret_cast<const float4*>(sb + j * 4), B1n = *reinterpret_cast<const float4*>(sb + 64 + j * 4);
;       const float4 C0n = *reinterpret_cast<const float4*>(sb + 128 + j * 4), C1n = *reinterpret_cast<const float4*>(sb + 192 + j * 4);
;       const float xdtn = sb[256 + prow], xrn = sb[272 + prow], an = sb[288];
;       __builtin_amdgcn_sched_barrier(0);
;       hs[0] = fmaf(a, hs[0], xdt * B0.x); hs[1] = fmaf(a, hs[1], xdt * B0.y); hs[2] = fmaf(a, hs[2], xdt * B0.z); hs[3] = fmaf(a, hs[3], xdt * B0.w);
;       hs[4] = fmaf(a, hs[4], xdt * B1.x); hs[5] = fmaf(a, hs[5], xdt * B1.y); hs[6] = fmaf(a, hs[6], xdt * B1.z); hs[7] = fmaf(a, hs[7], xdt * B1.w);
;       float y = hs[0] * C0.x + hs[1] * C0.y + hs[2] * C0.z + hs[3] * C0.w + hs[4] * C1.x + hs[5] * C1.y + hs[6] * C1.z + hs[7] * C1.w;
;       y = allreduce16(y);
;       y = fmaf(Dh, xr, y);
;       if (j == s) ykeep = y;
;       B0 = B0n; B1 = B1n; C0 = C0n; C1 = C1n; xdt = xdtn; xr = xrn; a = an;
;     }
;     Y[(size_t)(rowof(b, c * 16) + j) * 1024 + h * 64 + q * 16 + prow] = f2bf(ykeep);
;     if (c + 1 < NCH) lwrite((c + 1) & 1);
;     half_barrier(smem);
;   }
.Lsd_nofs1:
	s_waitcnt lgkmcnt(0)
	v_mfma_f32_16x16x4_f32 v[108:111], v124, v116, 0
	v_add_f32_dpp v177, v176, v176 row_shr:1 row_mask:0xf bank_mask:0xf bound_ctrl:1
	s_nop 1
	v_add_f32_dpp v178, v177, v177 row_shr:2 row_mask:0xf bank_mask:0xf bound_ctrl:1
	s_nop 1
	v_add_f32_dpp v179, v178, v178 row_shr:4 row_mask:0xf bank_mask:0xf bound_ctrl:1
	s_nop 1
	v_mfma_f32_16x16x4_f32 v[112:115], v116, v100, 0
	v_add_f32_dpp v180, v179, v179 row_shr:8 row_mask:0xf bank_mask:0xf bound_ctrl:1
	v_add_u32_e32 v78, s29, v64
	v_add_u32_e32 v80, s29, v65
	v_add_u32_e32 v81, s29, v66
	ds_write_b32 v78, v180
	ds_read_b128 v[156:159], v80
	v_mfma_f32_16x16x4_f32 v[108:111], v125, v117, v[108:111]
	ds_read_b32 v181, v81 offset:60
	v_add_u32_e32 v82, s29, v61
	v_add_u32_e32 v83, s29, v62
	ds_read_b32 v140, v83 offset:16896
	ds_read_b32 v141, v83 offset:16976
	ds_read_b32 v142, v83 offset:17056
	v_mfma_f32_16x16x4_f32 v[112:115], v117, v101, v[112:115]
	ds_read_b32 v143, v83 offset:17136
	ds_read_b32 v132, v82 offset:0
	ds_read_b32 v133, v82 offset:528
	ds_read_b32 v134, v82 offset:1056
	ds_read_b32 v135, v82 offset:1584
	ds_read_b32 v136, v82 offset:64
	v_mfma_f32_16x16x4_f32 v[108:111], v126, v118, v[108:111]
	ds_read_b32 v137, v82 offset:592
	ds_read_b32 v138, v82 offset:1120
	ds_read_b32 v139, v82 offset:1648
	ds_read_b32 v152, v83 offset:18176
	ds_read_b32 v153, v83 offset:18256
	ds_read_b32 v154, v83 offset:18336
	v_mfma_f32_16x16x4_f32 v[112:115], v118, v102, v[112:115]
	ds_read_b32 v155, v83 offset:18416
	s_waitcnt vmcnt(4)
	v_add_u32_e32 v18, s58, v69
	v_lshlrev_b32_e32 v12, 16, v184
	v_and_b32_e32 v13, 0xffff0000, v184
	v_lshlrev_b32_e32 v14, 16, v185
	v_mfma_f32_16x16x4_f32 v[108:111], v127, v119, v[108:111]
	v_and_b32_e32 v15, 0xffff0000, v185
	ds_write_b128 v18, v[12:15]
	v_lshlrev_b32_e32 v12, 16, v186
	v_and_b32_e32 v13, 0xffff0000, v186
	v_lshlrev_b32_e32 v14, 16, v187
	v_and_b32_e32 v15, 0xffff0000, v187
	v_mfma_f32_16x16x4_f32 v[112:115], v119, v103, v[112:115]
	ds_write_b128 v18, v[12:15] offset:16
	v_add_u32_e32 v18, s58, v70
	v_lshlrev_b32_e32 v12, 16, v188
	v_and_b32_e32 v13, 0xffff0000, v188
	v_lshlrev_b32_e32 v14, 16, v189
	v_and_b32_e32 v15, 0xffff0000, v189
	v_mfma_f32_16x16x4_f32 v[108:111], v128, v120, v[108:111]
	ds_write_b128 v18, v[12:15]
	v_lshlrev_b32_e32 v12, 16, v190
	v_and_b32_e32 v13, 0xffff0000, v190
	v_lshlrev_b32_e32 v14, 16, v191
	v_and_b32_e32 v15, 0xffff0000, v191
	ds_write_b128 v18, v[12:15] offset:16
	v_mfma_f32_16x16x4_f32 v[112:115], v120, v104, v[112:115]
	v_lshlrev_b32_e32 v9, 16, v94
	v_mul_f32_e32 v10, v95, v9
	v_add_u32_e32 v11, s58, v71
	ds_write_b32 v11, v10 offset:16896
	ds_write_b32 v11, v9 offset:18176
	v_mul_f32_e32 v9, v95, v46
	v_mfma_f32_16x16x4_f32 v[108:111], v129, v121, v[108:111]
	v_mul_f32_e32 v9, 0xbfb8aa3b, v9
	v_add_u32_e32 v11, s58, v72
	ds_write_b32 v11, v9 offset:19456
	s_waitcnt lgkmcnt(0)
	s_mov_b64 s[12:13], exec
	s_mov_b64 exec, 1
	ds_add_u32 v193, v195 offset:8
	s_mov_b64 exec, s[12:13]
	v_add_u32_e32 v194, 4, v194
	s_nop 3
	v_exp_f32_e32 v182, v181
	v_mfma_f32_16x16x4_f32 v[112:115], v121, v105, v[112:115]
	v_exp_f32_e32 v160, v156
	v_exp_f32_e32 v161, v157
	v_exp_f32_e32 v162, v158
	v_exp_f32_e32 v163, v159
	v_sub_f32_e32 v164, v181, v156
	v_sub_f32_e32 v165, v181, v157
	v_mfma_f32_16x16x4_f32 v[108:111], v130, v122, v[108:111]
	v_sub_f32_e32 v166, v181, v158
	v_sub_f32_e32 v167, v181, v159
	v_exp_f32_e32 v164, v164
	v_exp_f32_e32 v165, v165
	v_exp_f32_e32 v166, v166
	v_exp_f32_e32 v167, v167
	v_mfma_f32_16x16x4_f32 v[112:115], v122, v106, v[112:115]
	v_sub_f32_e32 v168, v180, v156
	v_sub_f32_e32 v169, v180, v157
	v_sub_f32_e32 v170, v180, v158
	v_sub_f32_e32 v171, v180, v159
	v_exp_f32_e32 v168, v168
	v_exp_f32_e32 v169, v169
	v_mfma_f32_16x16x4_f32 v[108:111], v131, v123, v[108:111]
	v_exp_f32_e32 v170, v170
	v_exp_f32_e32 v171, v171
	s_nop 0
	v_and_b32_e32 v168, v168, v74
	v_and_b32_e32 v169, v169, v75
	v_and_b32_e32 v170, v170, v76
	v_mfma_f32_16x16x4_f32 v[112:115], v123, v107, v[112:115]
	v_and_b32_e32 v171, v171, v77
	v_mul_f32_e32 v144, v164, v140
	v_mul_f32_e32 v145, v165, v141
	v_mul_f32_e32 v146, v166, v142
	v_mul_f32_e32 v147, v167, v143
	v_mul_f32_e32 v100, v182, v100
	v_mul_f32_e32 v101, v182, v101
	v_mul_f32_e32 v102, v182, v102
	v_mul_f32_e32 v103, v182, v103
	v_mul_f32_e32 v104, v182, v104
	v_mul_f32_e32 v105, v182, v105
	v_mul_f32_e32 v106, v182, v106
	v_mul_f32_e32 v107, v182, v107
	v_mul_f32_e32 v172, v108, v168
	v_mul_f32_e32 v173, v109, v169
	v_mul_f32_e32 v174, v110, v170
	v_mul_f32_e32 v175, v111, v171
	s_nop 3
	v_mul_f32_e32 v112, v112, v160
	v_mul_f32_e32 v113, v113, v161
	v_mul_f32_e32 v114, v114, v162
	v_mul_f32_e32 v115, v115, v163
	s_nop 1
	v_mfma_f32_16x16x4_f32 v[100:103], v132, v144, v[100:103]
	s_add_i32 s5, s4, 3
	s_min_i32 s5, s5, 0x80
	v_mfma_f32_16x16x4_f32 v[104:107], v136, v144, v[104:107]
	s_lshl_b32 s5, s5, 4
	s_add_i32 s5, s5, s11
	v_mfma_f32_16x16x4_f32 v[112:115], v172, v140, v[112:115]
	v_add_u32_e32 v8, s5, v45
	v_add_u32_e32 v84, s5, v47
	v_mfma_f32_16x16x4_f32 v[100:103], v133, v145, v[100:103]
	v_add_u32_e32 v88, s5, v48
	v_ashrrev_i32_e32 v9, 31, v8
	v_mfma_f32_16x16x4_f32 v[104:107], v137, v145, v[104:107]
	v_mad_i64_i32 v[84:85], s[12:13], v84, s0, v[30:31]
	v_mad_i64_i32 v[88:89], s[12:13], v88, s0, v[30:31]
	v_mfma_f32_16x16x4_f32 v[112:115], v173, v141, v[112:115]
	v_mad_i64_i32 v[10:11], s[12:13], v8, s0, v[26:27]
	v_lshl_add_u64 v[8:9], v[8:9], 4, s[40:41]
	v_mfma_f32_16x16x4_f32 v[100:103], v134, v146, v[100:103]
	global_load_dwordx4 v[84:87], v[84:85], off offset:512
	global_load_dwordx4 v[88:91], v[88:89], off offset:512
	v_mfma_f32_16x16x4_f32 v[104:107], v138, v146, v[104:107]
	global_load_ushort v92, v[10:11], off
	global_load_dword v93, v[8:9], off
	v_mfma_f32_16x16x4_f32 v[112:115], v174, v142, v[112:115]
	v_mfma_f32_16x16x4_f32 v[100:103], v135, v147, v[100:103]
	v_mfma_f32_16x16x4_f32 v[104:107], v139, v147, v[104:107]
	v_mfma_f32_16x16x4_f32 v[112:115], v175, v143, v[112:115]
	s_nop 7
	s_nop 3
	v_fmac_f32_e32 v112, v73, v152
	v_fmac_f32_e32 v113, v73, v153
	v_fmac_f32_e32 v114, v73, v154
	v_fmac_f32_e32 v115, v73, v155
	v_add_u32_e32 v78, s59, v67
	ds_write_b128 v78, v[112:115]

; __device__ __forceinline__ bf16_t f2bf(float f) { return (bf16_t)(pack2(f, 0.f) & 0xffffu); }
; __device__ __forceinline__ void ssd_scan_unit(CP p, int l, int u, char* smem) {
;     ...
;   for (int c = 0; c < NCH; ++c) {
;     if (c + 1 < NCH) gload(c + 1);
;     const float* cb = buf + (c & 1) * 16 * SST;
;     float ykeep = 0.f;
;     float4 B0 = *reinterpret_cast<const float4*>(cb + j * 4), B1 = *reinterpret_cast<const float4*>(cb + 64 + j * 4);
;     float4 C0 = *reinterpret_cast<const float4*>(cb + 128 + j * 4), C1 = *reinterpret_cast<const float4*>(cb + 192 + j * 4);
;     float xdt = cb[256 + prow], xr = cb[272 + prow], a = cb[288];
;     ...
;     Y[(size_t)(rowof(b, c * 16) + j) * 1024 + h * 64 + q * 16 + prow] = f2bf(ykeep);
.Ltw_donesd2:
	s_bitcmp1_b32 s4, 0
	s_cselect_b32 s29, 0x5000, 0
	s_cselect_b32 s58, 0, 0x5000
	s_add_i32 s29, s29, s63
	s_add_i32 s58, s58, s63
	s_add_i32 s59, s63, 0xc000
	s_add_i32 s14, s63, 0xa000
	v_add_u32_e32 v78, s29, v63
	ds_read_b32 v176, v78 offset:19456
	v_add_u32_e32 v79, s29, v60
	ds_read_b128 v[116:119], v79 offset:8448
	ds_read_b128 v[124:127], v79
	ds_read_b128 v[120:123], v79 offset:8512
	ds_read_b128 v[128:131], v79 offset:64
	s_cmp_lt_u32 s4, 2
	s_cbranch_scc1 .Lsd_nofs2
	v_add_u32_e32 v8, s14, v68
	ds_read_b32 v9, v8
	ds_read_b32 v10, v8 offset:1024
	ds_read_b32 v11, v8 offset:2048
	ds_read_b32 v12, v8 offset:3072
	s_add_i32 s5, s4, -2
	s_lshl_b32 s5, s5, 4
	s_add_i32 s5, s5, s11
	s_cmp_eq_u32 s4, 2
	s_cselect_b32 s5, s10, s5
	v_or_b32_e32 v14, s5, v44
	v_ashrrev_i32_e32 v15, 31, v14
	v_lshlrev_b64 v[14:15], 11, v[14:15]
	v_lshl_add_u64 v[14:15], v[28:29], 0, v[14:15]
	s_waitcnt lgkmcnt(0)
	v_add_f32_e32 v9, v9, v10
	v_add_f32_e32 v9, v9, v11
	v_add_f32_e32 v9, v9, v12
	v_cvt_pk_bf16_f32 v9, v9, s0
	global_store_short v[14:15], v9, off
; __device__ __forceinline__ bf16_t f2bf(float f) { return (bf16_t)(pack2(f, 0.f) & 0xffffu); }
; __device__ __forceinline__ void ssd_scan_unit(CP p, int l, int u, char* smem) {
;     ...
;   for (int c = 0; c < NCH; ++c) {
;     if (c + 1 < NCH) gload(c + 1);
;     const float* cb = buf + (c & 1) * 16 * SST;
;     float ykeep = 0.f;
;     float4 B0 = *reinterpret_cast<const float4*>(cb + j * 4), B1 = *reinterpret_cast<const float4*>(cb + 64 + j * 4);
;     float4 C0 = *reinterpret_cast<const float4*>(cb + 128 + j * 4), C1 = *reinterpret_cast<const float4*>(cb + 192 + j * 4);
;     float xdt = cb[256 + prow], xr = cb[272 + prow], a = cb[288];
; #pragma unroll 2
;     for (int s = 0; s < 16; ++s) {
;       const float* sb = cb + (s + 1) * SST;
;       const float4 B0n = *reinterpret_cast<const float4*>(sb + j * 4), B1n = *reinterpret_cast<const float4*>(sb + 64 + j * 4);
;       const float4 C0n = *reinterpret_cast<const float4*>(sb + 128 + j * 4), C1n = *reinterpret_cast<const float4*>(sb + 192 + j * 4);
;       const float xdtn = sb[256 + prow], xrn = sb[272 + prow], an = sb[288];
;       __builtin_amdgcn_sched_barrier(0);
;       hs[0] = fmaf(a, hs[0], xdt * B0.x); hs[1] = fmaf(a, hs[1], xdt * B0.y); hs[2] = fmaf(a, hs[2], xdt * B0.z); hs[3] = fmaf(a, hs[3], xdt * B0.w);
;       hs[4] = fmaf(a, hs[4], xdt * B1.x); hs[5] = fmaf(a, hs[5], xdt * B1.y); hs[6] = fmaf(a, hs[6], xdt * B1.z); hs[7] = fmaf(a, hs[7], xdt * B1.w);
;       float y = hs[0] * C0.x + hs[1] * C0.y + hs[2] * C0.z + hs[3] * C0.w + hs[4] * C1.x + hs[5] * C1.y + hs[6] * C1.z + hs[7] * C1.w;
;       y = allreduce16(y);
;       y = fmaf(Dh, xr, y);
;       if (j == s) ykeep = y;
;       B0 = B0n; B1 = B1n; C0 = C0n; C1 = C1n; xdt = xdtn; xr = xrn; a = an;
;     }
;     Y[(size_t)(rowof(b, c * 16) + j) * 1024 + h * 64 + q * 16 + prow] = f2bf(ykeep);
;     if (c + 1 < NCH) lwrite((c + 1) & 1);
;     half_barrier(smem);
;   }
.Lsd_nofs2:
	s_waitcnt lgkmcnt(0)
	v_mfma_f32_16x16x4_f32 v[108:111], v124, v116, 0
	v_add_f32_dpp v177, v176, v176 row_shr:1 row_mask:0xf bank_mask:0xf bound_ctrl:1
	s_nop 1
	v_add_f32_dpp v178, v177, v177 row_shr:2 row_mask:0xf bank_mask:0xf bound_ctrl:1
	s_nop 1
	v_add_f32_dpp v179, v178, v178 row_shr:4 row_mask:0xf bank_mask:0xf bound_ctrl:1
	s_nop 1
	v_mfma_f32_16x16x4_f32 v[112:115], v116, v100, 0
	v_add_f32_dpp v180, v179, v179 row_shr:8 row_mask:0xf bank_mask:0xf bound_ctrl:1
	v_add_u32_e32 v78, s29, v64
	v_add_u32_e32 v80, s29, v65
	v_add_u32_e32 v81, s29, v66
	ds_write_b32 v78, v180
	ds_read_b128 v[156:159], v80
	v_mfma_f32_16x16x4_f32 v[108:111], v125, v117, v[108:111]
	ds_read_b32 v181, v81 offset:60
	v_add_u32_e32 v82, s29, v61
	v_add_u32_e32 v83, s29, v62
	ds_read_b32 v140, v83 offset:16896
	ds_read_b32 v141, v83 offset:16976
	ds_read_b32 v142, v83 offset:17056
	v_mfma_f32_16x16x4_f32 v[112:115], v117, v101, v[112:115]
	ds_read_b32 v143, v83 offset:17136
	ds_read_b32 v132, v82 offset:0
	ds_read_b32 v133, v82 offset:528
	ds_read_b32 v134, v82 offset:1056
	ds_read_b32 v135, v82 offset:1584
	ds_read_b32 v136, v82 offset:64
	v_mfma_f32_16x16x4_f32 v[108:111], v126, v118, v[108:111]
	ds_read_b32 v137, v82 offset:592
	ds_read_b32 v138, v82 offset:1120
	ds_read_b32 v139, v82 offset:1648
	ds_read_b32 v152, v83 offset:18176
	ds_read_b32 v153, v83 offset:18256
	ds_read_b32 v154, v83 offset:18336
	v_mfma_f32_16x16x4_f32 v[112:115], v118, v102, v[112:115]
	ds_read_b32 v155, v83 offset:18416
	s_waitcnt vmcnt(4)
	v_add_u32_e32 v18, s58, v69
	v_lshlrev_b32_e32 v12, 16, v0
	v_and_b32_e32 v13, 0xffff0000, v0
	v_lshlrev_b32_e32 v14, 16, v1
	v_mfma_f32_16x16x4_f32 v[108:111], v127, v119, v[108:111]
	v_and_b32_e32 v15, 0xffff0000, v1
	ds_write_b128 v18, v[12:15]
	v_lshlrev_b32_e32 v12, 16, v2
	v_and_b32_e32 v13, 0xffff0000, v2
	v_lshlrev_b32_e32 v14, 16, v3
	v_and_b32_e32 v15, 0xffff0000, v3
	v_mfma_f32_16x16x4_f32 v[112:115], v119, v103, v[112:115]
	ds_write_b128 v18, v[12:15] offset:16
	v_add_u32_e32 v18, s58, v70
	v_lshlrev_b32_e32 v12, 16, v4
	v_and_b32_e32 v13, 0xffff0000, v4
	v_lshlrev_b32_e32 v14, 16, v5
	v_and_b32_e32 v15, 0xffff0000, v5
	v_mfma_f32_16x16x4_f32 v[108:111], v128, v120, v[108:111]
	ds_write_b128 v18, v[12:15]
	v_lshlrev_b32_e32 v12, 16, v6
	v_and_b32_e32 v13, 0xffff0000, v6
	v_lshlrev_b32_e32 v14, 16, v7
	v_and_b32_e32 v15, 0xffff0000, v7
	ds_write_b128 v18, v[12:15] offset:16
	v_mfma_f32_16x16x4_f32 v[112:115], v120, v104, v[112:115]
	v_lshlrev_b32_e32 v9, 16, v49
	v_mul_f32_e32 v10, v54, v9
	v_add_u32_e32 v11, s58, v71
	ds_write_b32 v11, v10 offset:16896
	ds_write_b32 v11, v9 offset:18176
	v_mul_f32_e32 v9, v54, v46
	v_mfma_f32_16x16x4_f32 v[108:111], v129, v121, v[108:111]
	v_mul_f32_e32 v9, 0xbfb8aa3b, v9
	v_add_u32_e32 v11, s58, v72
	ds_write_b32 v11, v9 offset:19456
	s_waitcnt lgkmcnt(0)
	s_mov_b64 s[12:13], exec
	s_mov_b64 exec, 1
	ds_add_u32 v193, v195 offset:8
	s_mov_b64 exec, s[12:13]
	v_add_u32_e32 v194, 4, v194
	s_nop 3
	v_exp_f32_e32 v182, v181
	v_mfma_f32_16x16x4_f32 v[112:115], v121, v105, v[112:115]
	v_exp_f32_e32 v160, v156
	v_exp_f32_e32 v161, v157
	v_exp_f32_e32 v162, v158
	v_exp_f32_e32 v163, v159
	v_sub_f32_e32 v164, v181, v156
	v_sub_f32_e32 v165, v181, v157
	v_mfma_f32_16x16x4_f32 v[108:111], v130, v122, v[108:111]
	v_sub_f32_e32 v166, v181, v158
	v_sub_f32_e32 v167, v181, v159
	v_exp_f32_e32 v164, v164
	v_exp_f32_e32 v165, v165
	v_exp_f32_e32 v166, v166
	v_exp_f32_e32 v167, v167
	v_mfma_f32_16x16x4_f32 v[112:115], v122, v106, v[112:115]
	v_sub_f32_e32 v168, v180, v156
	v_sub_f32_e32 v169, v180, v157
	v_sub_f32_e32 v170, v180, v158
	v_sub_f32_e32 v171, v180, v159
	v_exp_f32_e32 v168, v168
	v_exp_f32_e32 v169, v169
	v_mfma_f32_16x16x4_f32 v[108:111], v131, v123, v[108:111]
	v_exp_f32_e32 v170, v170
	v_exp_f32_e32 v171, v171
	s_nop 0
	v_and_b32_e32 v168, v168, v74
	v_and_b32_e32 v169, v169, v75
	v_and_b32_e32 v170, v170, v76
	v_mfma_f32_16x16x4_f32 v[112:115], v123, v107, v[112:115]
	v_and_b32_e32 v171, v171, v77
	v_mul_f32_e32 v144, v164, v140
	v_mul_f32_e32 v145, v165, v141
	v_mul_f32_e32 v146, v166, v142
	v_mul_f32_e32 v147, v167, v143
	v_mul_f32_e32 v100, v182, v100
	v_mul_f32_e32 v101, v182, v101
	v_mul_f32_e32 v102, v182, v102
	v_mul_f32_e32 v103, v182, v103
	v_mul_f32_e32 v104, v182, v104
	v_mul_f32_e32 v105, v182, v105
	v_mul_f32_e32 v106, v182, v106
	v_mul_f32_e32 v107, v182, v107
	v_mul_f32_e32 v172, v108, v168
	v_mul_f32_e32 v173, v109, v169
	v_mul_f32_e32 v174, v110, v170
	v_mul_f32_e32 v175, v111, v171
	s_nop 3
	v_mul_f32_e32 v112, v112, v160
	v_mul_f32_e32 v113, v113, v161
	v_mul_f32_e32 v114, v114, v162
	v_mul_f32_e32 v115, v115, v163
	s_nop 1
	v_mfma_f32_16x16x4_f32 v[100:103], v132, v144, v[100:103]
	s_add_i32 s5, s4, 3
	s_min_i32 s5, s5, 0x80
	v_mfma_f32_16x16x4_f32 v[104:107], v136, v144, v[104:107]
	s_lshl_b32 s5, s5, 4
	s_add_i32 s5, s5, s11
	v_mfma_f32_16x16x4_f32 v[112:115], v172, v140, v[112:115]
	v_add_u32_e32 v8, s5, v45
	v_add_u32_e32 v184, s5, v47
	v_mfma_f32_16x16x4_f32 v[100:103], v133, v145, v[100:103]
	v_add_u32_e32 v188, s5, v48
	v_ashrrev_i32_e32 v9, 31, v8
	v_mfma_f32_16x16x4_f32 v[104:107], v137, v145, v[104:107]
	v_mad_i64_i32 v[184:185], s[12:13], v184, s0, v[30:31]
	v_mad_i64_i32 v[188:189], s[12:13], v188, s0, v[30:31]
	v_mfma_f32_16x16x4_f32 v[112:115], v173, v141, v[112:115]
	v_mad_i64_i32 v[10:11], s[12:13], v8, s0, v[26:27]
	v_lshl_add_u64 v[8:9], v[8:9], 4, s[40:41]
	v_mfma_f32_16x16x4_f32 v[100:103], v134, v146, v[100:103]
	global_load_dwordx4 v[184:187], v[184:185], off offset:512
	global_load_dwordx4 v[188:191], v[188:189], off offset:512
	v_mfma_f32_16x16x4_f32 v[104:107], v138, v146, v[104:107]
	global_load_ushort v94, v[10:11], off
	global_load_dword v95, v[8:9], off
	v_mfma_f32_16x16x4_f32 v[112:115], v174, v142, v[112:115]
	v_mfma_f32_16x16x4_f32 v[100:103], v135, v147, v[100:103]
	v_mfma_f32_16x16x4_f32 v[104:107], v139, v147, v[104:107]
	v_mfma_f32_16x16x4_f32 v[112:115], v175, v143, v[112:115]
	s_nop 7
	s_nop 3
	v_fmac_f32_e32 v112, v73, v152
	v_fmac_f32_e32 v113, v73, v153
	v_fmac_f32_e32 v114, v73, v154
	v_fmac_f32_e32 v115, v73, v155
	v_add_u32_e32 v78, s59, v67
	ds_write_b128 v78, v[112:115]

; __device__ __forceinline__ int tidx() { int t = threadIdx.x & 255; asm volatile("" : "+v"(t)); return t; }
; __device__ __forceinline__ int half_id() { int t = (int)(threadIdx.x >> 8); asm volatile("" : "+v"(t)); return __builtin_amdgcn_readfirstlane(t); }
; #define LAS3 __attribute__((address_space(3)))
; __device__ __forceinline__ void half_barrier(char* smem_half) {
;   const int h = half_id();
;   LAS3 unsigned* cnt = (LAS3 unsigned*)(smem_half + (2 - h) * 65536 + 8 + h * 4);
;   asm volatile("s_waitcnt lgkmcnt(0)" ::: "memory");
;   if ((tidx() & 63) == 0) {
;     const unsigned old = __hip_atomic_fetch_add(cnt, 1u, __ATOMIC_RELAXED, __HIP_MEMORY_SCOPE_WORKGROUP);
;     const unsigned target = (old & ~3u) + 4u;
;     while (__hip_atomic_load(cnt, __ATOMIC_RELAXED, __HIP_MEMORY_SCOPE_WORKGROUP) < target) __builtin_amdgcn_s_sleep(1);
;   }
;   asm volatile("" ::: "memory");
; }
.Lsd_exit:
	s_waitcnt lgkmcnt(0)
	s_mov_b64 s[12:13], exec
	s_mov_b64 exec, 1
	ds_add_u32 v193, v195 offset:8
	s_mov_b64 exec, s[12:13]
	v_add_u32_e32 v194, 4, v194

; __device__ __forceinline__ bf16_t f2bf(float f) { return (bf16_t)(pack2(f, 0.f) & 0xffffu); }
; __device__ __forceinline__ void ssd_scan_unit(CP p, int l, int u, char* smem) {
;     ...
;     Y[(size_t)(rowof(b, c * 16) + j) * 1024 + h * 64 + q * 16 + prow] = f2bf(ykeep);
;     if (c + 1 < NCH) lwrite((c + 1) & 1);
;     half_barrier(smem);
;   }
.Lsd_bdone9:
	s_add_i32 s14, s63, 0xb000
	v_add_u32_e32 v8, s14, v68
	ds_read_b32 v9, v8
	ds_read_b32 v10, v8 offset:1024
	ds_read_b32 v11, v8 offset:2048
	ds_read_b32 v12, v8 offset:3072
	s_add_i32 s5, s11, 0x7f0
	v_or_b32_e32 v14, s5, v44
	v_ashrrev_i32_e32 v15, 31, v14
	v_lshlrev_b64 v[14:15], 11, v[14:15]
	v_lshl_add_u64 v[14:15], v[28:29], 0, v[14:15]
	s_waitcnt lgkmcnt(0)
	v_add_f32_e32 v9, v9, v10
	v_add_f32_e32 v9, v9, v11
	v_add_f32_e32 v9, v9, v12
	v_cvt_pk_bf16_f32 v9, v9, s0
	global_store_short v[14:15], v9, off
	s_add_i32 s14, s63, 0xc000
	v_add_u32_e32 v8, s14, v68
	ds_read_b32 v9, v8
	ds_read_b32 v10, v8 offset:1024
	ds_read_b32 v11, v8 offset:2048
	ds_read_b32 v12, v8 offset:3072
	s_add_i32 s5, s11, 0x800
	v_or_b32_e32 v14, s5, v44
	v_ashrrev_i32_e32 v15, 31, v14
	v_lshlrev_b64 v[14:15], 11, v[14:15]
	v_lshl_add_u64 v[14:15], v[28:29], 0, v[14:15]
	s_waitcnt lgkmcnt(0)
	v_add_f32_e32 v9, v9, v10
	v_add_f32_e32 v9, v9, v11
	v_add_f32_e32 v9, v9, v12
	v_cvt_pk_bf16_f32 v9, v9, s0
	global_store_short v[14:15], v9, off
	s_branch .LBB0_558

; __device__ __forceinline__ void run_phase(CP p, int ph, char* smem_full) {
;     ...
;         if (wk >= 0) {
;           for (int id = wk; id < 256 + 2 * ngu + 44 * 16; id += nwork) {
;             if (id < 256) conv_tile(p.in[7] + (size_t)l * D * D, WO, D, D, (id % 16) * 64, (id / 16) * 64, 0, smem);
;             else if (id < 256 + ngu) { const int k = id - 256; conv_tile(p.in[33] + (size_t)l * D * DFF, WA, D, DFF, (k % 16) * 64, (k / 16) * 64, 1, smem); }
;             else if (id < 256 + 2 * ngu) { const int k = id - 256 - ngu; conv_tile(p.in[34] + (size_t)l * D * DFF, WA, D, DFF, (k % 16) * 64, (k / 16) * 64, 2, smem); }
;             else { const int k = id - 256 - 2 * ngu; conv_tile(p.in[35] + (size_t)l * DFF * D, WB, DFF, D, (k % 44) * 64, (k / 44) * 64, 0, smem); }
;           }
.LBB0_589:
	s_addk_i32 s10, 0x48
	s_cmpk_gt_i32 s10, 0x93f
	s_cbranch_scc1 .LBB0_649
